# out-projection -> mid rowwise barrier also per XCC; the ACT-over-PROJ/CONCAT overwrite is ordered by a counted wait at the mid rowwise -> gate|up barrier
# baseline (speedup 1.0000x reference)
; __device__ __forceinline__ unsigned xb_ld(unsigned* p)              { return __hip_atomic_load(p, __ATOMIC_RELAXED, __HIP_MEMORY_SCOPE_AGENT); }
; __device__ __forceinline__ unsigned xb_add(unsigned* p, unsigned v) { return __hip_atomic_fetch_add(p, v, __ATOMIC_RELAXED, __HIP_MEMORY_SCOPE_AGENT); }
; #define XB_SPIN(cond, bar) do { unsigned _sp = 0; while (cond) { __builtin_amdgcn_s_sleep(1); \
;     if ((++_sp & 255u) == 0u) { if (xb_ld(&(bar)[XB_TMO])) break; if (_sp > XB_SPIN_CAP) { atomicAdd(&(bar)[XB_TMO], 1u); break; } } } } while (0)
; __device__ __forceinline__ void xcd_barrier(const XcdBarrier& b) {
;     asm volatile("s_waitcnt vmcnt(0)" ::: "memory");
;     __syncthreads();
;     if (threadIdx.x == 0) {
;         unsigned* bar = b.bar;
;         __builtin_amdgcn_s_waitcnt(0);
;         unsigned nloc = b.st[0], nx = b.st[1];
;         if (nloc == 0u) { xcd_barrier_complete(bar, b.x, nloc, nx); b.st[0] = nloc; b.st[1] = nx; }
;         const unsigned old = xb_add(&bar[XB_XSUB(b.x)], 1u);
;         const unsigned gen = old / nloc;
;         if (old + 1u == (gen + 1u) * nloc) {
;             __builtin_amdgcn_fence(__ATOMIC_RELEASE, "agent");
;             asm volatile("s_waitcnt vmcnt(0)" ::: "memory");
;             const unsigned og = xb_add(&bar[XB_TOP], 1u);
;             const unsigned tg = og / nx;
;             if (og + 1u == (tg + 1u) * nx) xb_add(&bar[XB_TOPGEN], 1u);
;             else XB_SPIN(xb_ld(&bar[XB_TOPGEN]) == tg, bar);
;             __builtin_amdgcn_fence(__ATOMIC_ACQUIRE, "agent");
;             xb_add(&bar[XB_XGEN(b.x)], 1u);
;             asm volatile("s_waitcnt vmcnt(0)" ::: "memory");
;         } else {
;             XB_SPIN(xb_ld(&bar[XB_XGEN(b.x)]) == gen, bar);
.LBB0_482:
	s_andn2_saveexec_b64 s[16:17], s[36:37]
	s_cbranch_execz .LBB0_502
	v_readfirstlane_b32 s100, v247
	s_nop 3
	s_cmp_eq_u32 s100, 0
	s_cbranch_scc1 .Lxb_global_3
	v_readlane_b32 s100, v245, 18
	v_readlane_b32 s101, v245, 19
	v_mov_b32_e32 v251, 0
	v_mov_b32_e32 v250, 1
	s_nop 4
	global_atomic_add v251, v250, s[100:101]
	global_atomic_add v251, v250, s[94:95] offset:800
	s_waitcnt vmcnt(2)
	s_branch .LBB0_502
.Lxb_global_3:
	s_mov_b64 s[16:17], exec
	buffer_wbl2 sc1
	s_waitcnt lgkmcnt(0)
	s_waitcnt vmcnt(0)
	v_mbcnt_lo_u32_b32 v0, s16, 0
	v_mbcnt_hi_u32_b32 v0, s17, v0
	v_cmp_eq_u32_e32 vcc, 0, v0
	s_and_saveexec_b64 s[36:37], vcc
	s_cbranch_execz .LBB0_485
	s_bcnt1_i32_b64 s16, s[16:17]
	v_mov_b32_e32 v3, s16
	v_readlane_b32 s16, v245, 20
	v_readlane_b32 s17, v245, 21
	s_nop 4
	global_atomic_add v3, v1, v3, s[16:17] sc0
.LBB0_485:
	s_or_b64 exec, exec, s[36:37]
	s_waitcnt vmcnt(0)
	v_readfirstlane_b32 s16, v3
	v_sub_u32_e32 v4, 0, v2
	s_mov_b64 s[38:39], -1
	v_add_u32_e32 v3, s16, v0
	v_cvt_f32_u32_e32 v0, v2
	v_readlane_b32 s16, v245, 22
	v_readlane_b32 s17, v245, 23
	v_rcp_iflag_f32_e32 v0, v0
	s_nop 0
	v_mul_f32_e32 v0, 0x4f7ffffe, v0
	v_cvt_u32_f32_e32 v0, v0
	v_mul_lo_u32 v4, v4, v0
	v_mul_hi_u32 v4, v0, v4
	v_add_u32_e32 v0, v0, v4
	v_mul_hi_u32 v0, v3, v0
	v_mul_lo_u32 v4, v0, v2
	v_sub_u32_e32 v4, v3, v4
	v_cmp_ge_u32_e32 vcc, v4, v2
	v_add_u32_e32 v5, 1, v0
	v_add_u32_e32 v3, 1, v3
	v_cndmask_b32_e32 v0, v0, v5, vcc
	v_sub_u32_e32 v5, v4, v2
	v_cndmask_b32_e32 v4, v4, v5, vcc
	v_cmp_ge_u32_e32 vcc, v4, v2
	v_add_u32_e32 v4, 1, v0
	s_nop 0
	v_cndmask_b32_e32 v0, v0, v4, vcc
	v_mul_lo_u32 v4, v2, v0
	v_add_u32_e32 v2, v4, v2
	v_cmp_ne_u32_e32 vcc, v3, v2
	s_mov_b64 s[98:99], vcc
	v_mov_b64_e32 v[2:3], s[16:17]
	s_and_saveexec_b64 s[36:37], vcc
	s_cbranch_execz .LBB0_497
	v_readlane_b32 s16, v245, 18
	v_readlane_b32 s17, v245, 19
	s_nop 4
	global_load_dword v2, v1, s[16:17] sc1
	s_mov_b64 s[16:17], 0
	s_waitcnt vmcnt(0)
	v_cmp_eq_u32_e32 vcc, v2, v250
	s_and_saveexec_b64 s[38:39], vcc
	s_cbranch_execz .LBB0_496
	s_mov_b32 s23, 1
	s_mov_b64 s[40:41], 0
	s_branch .LBB0_489

; __device__ __forceinline__ unsigned xb_ld(unsigned* p)              { return __hip_atomic_load(p, __ATOMIC_RELAXED, __HIP_MEMORY_SCOPE_AGENT); }
; __device__ __forceinline__ unsigned xb_add(unsigned* p, unsigned v) { return __hip_atomic_fetch_add(p, v, __ATOMIC_RELAXED, __HIP_MEMORY_SCOPE_AGENT); }
; #define XB_SPIN(cond, bar) do { unsigned _sp = 0; while (cond) { __builtin_amdgcn_s_sleep(1); \
;     if ((++_sp & 255u) == 0u) { if (xb_ld(&(bar)[XB_TMO])) break; if (_sp > XB_SPIN_CAP) { atomicAdd(&(bar)[XB_TMO], 1u); break; } } } } while (0)
; __device__ __forceinline__ void xcd_barrier(const XcdBarrier& b) {
;     asm volatile("s_waitcnt vmcnt(0)" ::: "memory");
;     __syncthreads();
;     if (threadIdx.x == 0) {
;         unsigned* bar = b.bar;
;         __builtin_amdgcn_s_waitcnt(0);
;         unsigned nloc = b.st[0], nx = b.st[1];
;         if (nloc == 0u) { xcd_barrier_complete(bar, b.x, nloc, nx); b.st[0] = nloc; b.st[1] = nx; }
;         const unsigned old = xb_add(&bar[XB_XSUB(b.x)], 1u);
;         const unsigned gen = old / nloc;
;         if (old + 1u == (gen + 1u) * nloc) {
;             __builtin_amdgcn_fence(__ATOMIC_RELEASE, "agent");
;             asm volatile("s_waitcnt vmcnt(0)" ::: "memory");
;             const unsigned og = xb_add(&bar[XB_TOP], 1u);
;             const unsigned tg = og / nx;
;             if (og + 1u == (tg + 1u) * nx) xb_add(&bar[XB_TOPGEN], 1u);
;             else XB_SPIN(xb_ld(&bar[XB_TOPGEN]) == tg, bar);
;             __builtin_amdgcn_fence(__ATOMIC_ACQUIRE, "agent");
;             xb_add(&bar[XB_XGEN(b.x)], 1u);
;             asm volatile("s_waitcnt vmcnt(0)" ::: "memory");
;         } else {
;             XB_SPIN(xb_ld(&bar[XB_XGEN(b.x)]) == gen, bar);
.LBB0_551:
	s_andn2_saveexec_b64 s[16:17], s[36:37]
	s_cbranch_execz .LBB0_571
	v_readfirstlane_b32 s100, v247
	s_nop 3
	s_cmp_eq_u32 s100, 0
	s_cbranch_scc1 .Lxb_global_1
	s_waitcnt lgkmcnt(0)
	v_readfirstlane_b32 s100, v2
	v_readlane_b32 s101, v244, 21
	s_nop 3
	s_add_i32 s101, s101, 1
	s_mul_i32 s100, s100, s101
	s_mov_b32 s101, 0x100000
	v_mov_b32_e32 v251, 0
.Lxb_lazy_poll:
	global_load_dword v250, v251, s[94:95] offset:800 sc1
	s_waitcnt vmcnt(0)
	v_cmp_gt_u32_e32 vcc, s100, v250
	s_cbranch_vccz .Lxb_lazy_done
	s_sleep 1
	s_sub_u32 s101, s101, 1
	s_cmp_lg_u32 s101, 0
	s_cbranch_scc1 .Lxb_lazy_poll
.Lxb_lazy_done:
	v_readlane_b32 s100, v245, 18
	v_readlane_b32 s101, v245, 19
	v_mov_b32_e32 v251, 0
	v_mov_b32_e32 v250, 1
	s_nop 4
	global_atomic_add v251, v250, s[100:101]
	s_waitcnt vmcnt(1)
	s_branch .LBB0_571
